# 8-phase K-loops (GEMM1 fp8, GEMM1 bf16, GEMM2): the wave half that runs one phase ahead waits vmcnt(8) at the END of the MFMA segment instead of before it (its refills have one more phase before their
# speedup vs baseline: 1.0044x; 1.0044x over previous
; #define PG8_STAGE(bufoff, gbase, voff) do { _Pragma("unroll") for (int _i = 0; _i < 2; ++_i) \
;         __builtin_amdgcn_global_load_lds((const unsigned*)((const char*)(gbase) + (voff)[_i]), (PG8_LAS unsigned*)(lds + (bufoff) + ldsw + _i * 8192), 16, 0, 0); } while (0)
; #define PG8_LDA(dst, b, h) do { _Pragma("unroll") for (int m = 0; m < 4; ++m) _Pragma("unroll") for (int k = 0; k < 2; ++k) dst[m][k] = *(const PG8_LAS bf16x8*)(lds + PG8_SA(b, h) + aoff + m * 2048 + k * KOFF); } while (0)
; #define PG8_LDB(dst, b, h) do { _Pragma("unroll") for (int n = 0; n < 2; ++n) _Pragma("unroll") for (int k = 0; k < 2; ++k) dst[n][k] = *(const PG8_LAS bf16x8*)(lds + PG8_SB(b, h) + boff + n * 2048 + k * KOFF); } while (0)
; #define PG8_WAIT_V(n) asm volatile("s_waitcnt vmcnt(" #n ")" ::: "memory")
; #define PG8_WAIT_L(n) asm volatile("s_waitcnt lgkmcnt(" #n ")" ::: "memory")
; #define PG8_BAR __builtin_amdgcn_s_barrier()
; #define PG8_SCHED __builtin_amdgcn_sched_barrier(0)
; template <class Epi, class Sched, bool ALIGN_EPI = false, bool SP2 = false, bool F8 = false>
; __device__ __forceinline__ void gemm_phase(PG8_LAS unsigned char* lds, const Gemm g, const Sched& S, const Epi& E) {
;     ...
;             PG8_LDB(B0, 0, 0); PG8_LDB(B1, 0, 1); PG8_SCHED; PG8_LDA(At, 0, 0); PG8_STAGE(PG8_SA(1, 1), a1 + hstep, voffA);
;             PG8_WAIT_V(8); PG8_WAIT_L(0); PG8_BAR; PG8_MMA(0, 0, At, B0); PG8_MMA(0, 1, At, B1); PG8_BAR; PG8_SCHED;
;             PG8_LDA(At, 0, 1); PG8_STAGE(PG8_SB(0, 0), b2, voffB); PG8_STAGE(PG8_SB(0, 1), b2 + hstep, voffB); PG8_STAGE(PG8_SA(0, 0), a2, voffA);
;             PG8_WAIT_V(8); PG8_WAIT_L(0); PG8_BAR; PG8_MMA(1, 0, At, B0); PG8_MMA(1, 1, At, B1); PG8_BAR; PG8_SCHED;
.LBB0_387:
	s_or_b32 s34, s46, 1
	s_lshl_b64 s[88:89], s[34:35], 7
	s_add_i32 s34, s46, 2
	s_lshl_b64 vcc, s[34:35], 7
	s_add_u32 s38, s4, vcc_lo
	s_addc_u32 s39, s5, vcc_hi
	s_and_b64 s[86:87], s[84:85], exec
	s_cselect_b32 s87, s71, s39
	s_cselect_b32 s86, s70, s38
	s_add_u32 s38, s6, vcc_lo
	s_addc_u32 s39, s7, vcc_hi
	s_and_b64 s[84:85], s[84:85], exec
	s_cselect_b32 s85, s73, s39
	s_cselect_b32 s84, s72, s38
	s_add_i32 s38, 0, 0x10000
	v_add_u32_e32 v140, s38, v142
	s_add_i32 s39, 0, 0x14000
	ds_read_b128 v[136:139], v140
	ds_read_b128 v[144:147], v140 offset:1024
	ds_read_b128 v[148:151], v140 offset:2048
	ds_read_b128 v[152:155], v140 offset:3072
	v_add_u32_e32 v140, s39, v142
	ds_read_b128 v[156:159], v140
	ds_read_b128 v[188:191], v140 offset:1024
	ds_read_b128 v[192:195], v140 offset:2048
	ds_read_b128 v[196:199], v140 offset:3072
	s_add_u32 s88, s33, s88
	s_addc_u32 s89, s45, s89
	v_lshl_add_u64 v[140:141], s[88:89], 0, v[164:165]
	s_add_i32 m0, s1, 0xc000
	ds_read_b128 v[210:213], v143
	ds_read_b128 v[214:217], v143 offset:1024
	ds_read_b128 v[218:221], v143 offset:2048
	ds_read_b128 v[222:225], v143 offset:3072
	ds_read_b128 v[226:229], v143 offset:4096
	ds_read_b128 v[230:233], v143 offset:5120
	ds_read_b128 v[234:237], v143 offset:6144
	ds_read_b128 v[238:241], v143 offset:7168
	global_load_lds_dwordx4 v[140:141], off
	v_lshl_add_u64 v[140:141], s[88:89], 0, v[168:169]
	s_add_i32 m0, s1, 0xe000
	s_nop 0
	global_load_lds_dwordx4 v[140:141], off
	s_and_b64 vcc, exec, s[62:63]
	s_cbranch_vccz .Ldefer_b16_0
	s_waitcnt vmcnt(8)
.Ldefer_b16_0:
	s_waitcnt lgkmcnt(0)
	s_barrier
	s_setprio 1
	s_waitcnt lgkmcnt(0)
	v_mfma_f32_16x16x32_bf16 v[126:129], v[136:139], v[210:213], v[126:129]
	v_mfma_f32_16x16x32_bf16 v[122:125], v[148:151], v[210:213], v[122:125]
	v_mfma_f32_16x16x32_bf16 v[110:113], v[136:139], v[218:221], v[110:113]
	v_mfma_f32_16x16x32_bf16 v[106:109], v[148:151], v[218:221], v[106:109]
	v_mfma_f32_16x16x32_bf16 v[94:97], v[136:139], v[226:229], v[94:97]
	v_mfma_f32_16x16x32_bf16 v[90:93], v[148:151], v[226:229], v[90:93]
	v_mfma_f32_16x16x32_bf16 v[78:81], v[136:139], v[234:237], v[78:81]
	v_mfma_f32_16x16x32_bf16 v[74:77], v[148:151], v[234:237], v[74:77]
	v_mfma_f32_16x16x32_bf16 v[126:129], v[144:147], v[214:217], v[126:129]
	v_mfma_f32_16x16x32_bf16 v[122:125], v[152:155], v[214:217], v[122:125]
	v_mfma_f32_16x16x32_bf16 v[110:113], v[144:147], v[222:225], v[110:113]
	v_mfma_f32_16x16x32_bf16 v[106:109], v[152:155], v[222:225], v[106:109]
	v_mfma_f32_16x16x32_bf16 v[94:97], v[144:147], v[230:233], v[94:97]
	v_mfma_f32_16x16x32_bf16 v[90:93], v[152:155], v[230:233], v[90:93]
	v_mfma_f32_16x16x32_bf16 v[78:81], v[144:147], v[238:241], v[78:81]
	v_mfma_f32_16x16x32_bf16 v[74:77], v[152:155], v[238:241], v[74:77]
	s_setprio 0
	s_setprio 1
	v_mfma_f32_16x16x32_bf16 v[118:121], v[156:159], v[210:213], v[118:121]
	v_mfma_f32_16x16x32_bf16 v[114:117], v[192:195], v[210:213], v[114:117]
	v_mfma_f32_16x16x32_bf16 v[102:105], v[156:159], v[218:221], v[102:105]
	v_mfma_f32_16x16x32_bf16 v[98:101], v[192:195], v[218:221], v[98:101]
	v_mfma_f32_16x16x32_bf16 v[86:89], v[156:159], v[226:229], v[86:89]
	v_mfma_f32_16x16x32_bf16 v[82:85], v[192:195], v[226:229], v[82:85]
	v_mfma_f32_16x16x32_bf16 v[70:73], v[156:159], v[234:237], v[70:73]
	v_mfma_f32_16x16x32_bf16 v[66:69], v[192:195], v[234:237], v[66:69]
	v_mfma_f32_16x16x32_bf16 v[118:121], v[188:191], v[214:217], v[118:121]
	v_mfma_f32_16x16x32_bf16 v[114:117], v[196:199], v[214:217], v[114:117]
	v_mfma_f32_16x16x32_bf16 v[102:105], v[188:191], v[222:225], v[102:105]
	v_mfma_f32_16x16x32_bf16 v[98:101], v[196:199], v[222:225], v[98:101]
	v_mfma_f32_16x16x32_bf16 v[86:89], v[188:191], v[230:233], v[86:89]
	v_mfma_f32_16x16x32_bf16 v[82:85], v[196:199], v[230:233], v[82:85]
	v_mfma_f32_16x16x32_bf16 v[70:73], v[188:191], v[238:241], v[70:73]
	v_mfma_f32_16x16x32_bf16 v[66:69], v[196:199], v[238:241], v[66:69]
	s_setprio 0
	s_waitcnt vmcnt(8)
	s_barrier
	s_add_i32 s38, s38, s0
	v_lshl_add_u64 v[140:141], s[84:85], 0, v[166:167]
	s_mov_b32 m0, s38
	ds_read_b128 v[210:213], v143 offset:16384
	ds_read_b128 v[214:217], v143 offset:17408
	ds_read_b128 v[218:221], v143 offset:18432
	ds_read_b128 v[222:225], v143 offset:19456
	ds_read_b128 v[226:229], v143 offset:20480
	ds_read_b128 v[230:233], v143 offset:21504
	ds_read_b128 v[234:237], v143 offset:22528
	ds_read_b128 v[238:241], v143 offset:23552
	global_load_lds_dwordx4 v[140:141], off
	s_add_i32 m0, s38, 0x2000
	s_add_u32 s88, s84, 0x80000
	v_lshl_add_u64 v[160:161], s[84:85], 0, v[170:171]
	s_addc_u32 s89, s85, 0
	s_add_i32 s38, s39, s0
	global_load_lds_dwordx4 v[160:161], off
	v_lshl_add_u64 v[242:243], s[88:89], 0, v[166:167]
	s_mov_b32 m0, s38
	v_lshl_add_u64 v[244:245], s[86:87], 0, v[168:169]
	global_load_lds_dwordx4 v[242:243], off
	v_lshl_add_u64 v[242:243], s[88:89], 0, v[170:171]
	s_add_i32 m0, s38, 0x2000
	s_nop 0
	global_load_lds_dwordx4 v[242:243], off
	v_lshl_add_u64 v[242:243], s[86:87], 0, v[164:165]
	s_mov_b32 m0, s1
	s_nop 0
	global_load_lds_dwordx4 v[242:243], off
	s_mov_b32 m0, s36
	s_nop 0
	global_load_lds_dwordx4 v[244:245], off
	s_and_b64 vcc, exec, s[62:63]
	s_cbranch_vccz .Ldefer_b16_1
	s_waitcnt vmcnt(8)
; #define PG8_STAGE(bufoff, gbase, voff) do { _Pragma("unroll") for (int _i = 0; _i < 2; ++_i) \
;         __builtin_amdgcn_global_load_lds((const unsigned*)((const char*)(gbase) + (voff)[_i]), (PG8_LAS unsigned*)(lds + (bufoff) + ldsw + _i * 8192), 16, 0, 0); } while (0)
; #define PG8_LDA(dst, b, h) do { _Pragma("unroll") for (int m = 0; m < 4; ++m) _Pragma("unroll") for (int k = 0; k < 2; ++k) dst[m][k] = *(const PG8_LAS bf16x8*)(lds + PG8_SA(b, h) + aoff + m * 2048 + k * KOFF); } while (0)
; #define PG8_LDB(dst, b, h) do { _Pragma("unroll") for (int n = 0; n < 2; ++n) _Pragma("unroll") for (int k = 0; k < 2; ++k) dst[n][k] = *(const PG8_LAS bf16x8*)(lds + PG8_SB(b, h) + boff + n * 2048 + k * KOFF); } while (0)
; #define PG8_WAIT_V(n) asm volatile("s_waitcnt vmcnt(" #n ")" ::: "memory")
; #define PG8_WAIT_L(n) asm volatile("s_waitcnt lgkmcnt(" #n ")" ::: "memory")
; #define PG8_BAR __builtin_amdgcn_s_barrier()
; #define PG8_SCHED __builtin_amdgcn_sched_barrier(0)
; template <class Epi, class Sched, bool ALIGN_EPI = false, bool SP2 = false, bool F8 = false>
; __device__ __forceinline__ void gemm_phase(PG8_LAS unsigned char* lds, const Gemm g, const Sched& S, const Epi& E) {
;     ...
;             PG8_WAIT_V(8); PG8_WAIT_L(0); PG8_BAR; PG8_MMA(1, 0, At, B0); PG8_MMA(1, 1, At, B1); PG8_BAR; PG8_SCHED;
;             PG8_LDB(B0, 1, 0); PG8_LDB(B1, 1, 1); PG8_SCHED; PG8_LDA(At, 1, 0); PG8_STAGE(PG8_SA(0, 1), a2 + hstep, voffA);
.Ldefer_b16_1:
	s_waitcnt lgkmcnt(0)
	s_barrier
	s_setprio 1
	s_waitcnt lgkmcnt(0)
	v_mfma_f32_16x16x32_bf16 v[62:65], v[136:139], v[210:213], v[62:65]
	v_mfma_f32_16x16x32_bf16 v[58:61], v[148:151], v[210:213], v[58:61]
	v_mfma_f32_16x16x32_bf16 v[46:49], v[136:139], v[218:221], v[46:49]
	v_mfma_f32_16x16x32_bf16 v[42:45], v[148:151], v[218:221], v[42:45]
	v_mfma_f32_16x16x32_bf16 v[30:33], v[136:139], v[226:229], v[30:33]
	v_mfma_f32_16x16x32_bf16 v[26:29], v[148:151], v[226:229], v[26:29]
	v_mfma_f32_16x16x32_bf16 v[14:17], v[136:139], v[234:237], v[14:17]
	v_mfma_f32_16x16x32_bf16 v[10:13], v[148:151], v[234:237], v[10:13]
	v_mfma_f32_16x16x32_bf16 v[62:65], v[144:147], v[214:217], v[62:65]
	v_mfma_f32_16x16x32_bf16 v[58:61], v[152:155], v[214:217], v[58:61]
	v_mfma_f32_16x16x32_bf16 v[46:49], v[144:147], v[222:225], v[46:49]
	v_mfma_f32_16x16x32_bf16 v[42:45], v[152:155], v[222:225], v[42:45]
	v_mfma_f32_16x16x32_bf16 v[30:33], v[144:147], v[230:233], v[30:33]
	v_mfma_f32_16x16x32_bf16 v[26:29], v[152:155], v[230:233], v[26:29]
	v_mfma_f32_16x16x32_bf16 v[14:17], v[144:147], v[238:241], v[14:17]
	v_mfma_f32_16x16x32_bf16 v[10:13], v[152:155], v[238:241], v[10:13]
	s_setprio 0
	s_setprio 1
	v_mfma_f32_16x16x32_bf16 v[54:57], v[156:159], v[210:213], v[54:57]
	v_mfma_f32_16x16x32_bf16 v[50:53], v[192:195], v[210:213], v[50:53]
	v_mfma_f32_16x16x32_bf16 v[38:41], v[156:159], v[218:221], v[38:41]
	v_mfma_f32_16x16x32_bf16 v[34:37], v[192:195], v[218:221], v[34:37]
	v_mfma_f32_16x16x32_bf16 v[22:25], v[156:159], v[226:229], v[22:25]
	v_mfma_f32_16x16x32_bf16 v[18:21], v[192:195], v[226:229], v[18:21]
	v_mfma_f32_16x16x32_bf16 v[6:9], v[156:159], v[234:237], v[6:9]
	v_mfma_f32_16x16x32_bf16 v[2:5], v[192:195], v[234:237], v[2:5]
	v_mfma_f32_16x16x32_bf16 v[54:57], v[188:191], v[214:217], v[54:57]
	v_mfma_f32_16x16x32_bf16 v[50:53], v[196:199], v[214:217], v[50:53]
	v_mfma_f32_16x16x32_bf16 v[38:41], v[188:191], v[222:225], v[38:41]
	v_mfma_f32_16x16x32_bf16 v[34:37], v[196:199], v[222:225], v[34:37]
	v_mfma_f32_16x16x32_bf16 v[22:25], v[188:191], v[230:233], v[22:25]
	v_mfma_f32_16x16x32_bf16 v[18:21], v[196:199], v[230:233], v[18:21]
	v_mfma_f32_16x16x32_bf16 v[6:9], v[188:191], v[238:241], v[6:9]
	v_mfma_f32_16x16x32_bf16 v[2:5], v[196:199], v[238:241], v[2:5]
	s_setprio 0
	s_waitcnt vmcnt(8)
	s_barrier
	s_add_i32 s38, 0, 0x18000
	s_add_i32 s39, 0, 0x1c000
	v_add_u32_e32 v152, s38, v142
	v_add_u32_e32 v172, s39, v142
	ds_read_b128 v[136:139], v152
	ds_read_b128 v[144:147], v152 offset:1024
	ds_read_b128 v[148:151], v152 offset:2048
	ds_read_b128 v[152:155], v152 offset:3072
	ds_read_b128 v[156:159], v172
	ds_read_b128 v[188:191], v172 offset:1024
	ds_read_b128 v[192:195], v172 offset:2048
	ds_read_b128 v[196:199], v172 offset:3072
	s_add_u32 s86, s86, 0x80000
	s_addc_u32 s87, s87, 0
	s_mov_b32 m0, s74
	v_lshl_add_u64 v[246:247], s[86:87], 0, v[164:165]
	ds_read_b128 v[210:213], v143 offset:32768
	ds_read_b128 v[214:217], v143 offset:33792
	ds_read_b128 v[218:221], v143 offset:34816
	ds_read_b128 v[222:225], v143 offset:35840
	ds_read_b128 v[226:229], v143 offset:36864
	ds_read_b128 v[230:233], v143 offset:37888
	ds_read_b128 v[234:237], v143 offset:38912
	ds_read_b128 v[238:241], v143 offset:39936
	global_load_lds_dwordx4 v[246:247], off
	v_lshl_add_u64 v[246:247], s[86:87], 0, v[168:169]
	s_mov_b32 m0, s75
	s_nop 0
	global_load_lds_dwordx4 v[246:247], off
	s_and_b64 vcc, exec, s[62:63]
	s_cbranch_vccz .Ldefer_b16_2
	s_waitcnt vmcnt(8)
; #define PG8_STAGE(bufoff, gbase, voff) do { _Pragma("unroll") for (int _i = 0; _i < 2; ++_i) \
;         __builtin_amdgcn_global_load_lds((const unsigned*)((const char*)(gbase) + (voff)[_i]), (PG8_LAS unsigned*)(lds + (bufoff) + ldsw + _i * 8192), 16, 0, 0); } while (0)
; #define PG8_LDA(dst, b, h) do { _Pragma("unroll") for (int m = 0; m < 4; ++m) _Pragma("unroll") for (int k = 0; k < 2; ++k) dst[m][k] = *(const PG8_LAS bf16x8*)(lds + PG8_SA(b, h) + aoff + m * 2048 + k * KOFF); } while (0)
; #define PG8_WAIT_V(n) asm volatile("s_waitcnt vmcnt(" #n ")" ::: "memory")
; #define PG8_WAIT_L(n) asm volatile("s_waitcnt lgkmcnt(" #n ")" ::: "memory")
; #define PG8_BAR __builtin_amdgcn_s_barrier()
; #define PG8_SCHED __builtin_amdgcn_sched_barrier(0)
; template <class Epi, class Sched, bool ALIGN_EPI = false, bool SP2 = false, bool F8 = false>
; __device__ __forceinline__ void gemm_phase(PG8_LAS unsigned char* lds, const Gemm g, const Sched& S, const Epi& E) {
;     ...
;             PG8_WAIT_V(8); PG8_WAIT_L(0); PG8_BAR; PG8_MMA(0, 0, At, B0); PG8_MMA(0, 1, At, B1); PG8_BAR; PG8_SCHED;
;             PG8_LDA(At, 1, 1); PG8_STAGE(PG8_SB(1, 0), b3, voffB); PG8_STAGE(PG8_SB(1, 1), b3 + hstep, voffB); PG8_STAGE(PG8_SA(1, 0), a3, voffA);
;             PG8_WAIT_V(8); PG8_WAIT_L(0); PG8_BAR; PG8_MMA(1, 0, At, B0); PG8_MMA(1, 1, At, B1); PG8_BAR; PG8_SCHED;
.Ldefer_b16_2:
	s_waitcnt lgkmcnt(0)
	s_barrier
	s_setprio 1
	s_waitcnt lgkmcnt(0)
	v_mfma_f32_16x16x32_bf16 v[126:129], v[136:139], v[210:213], v[126:129]
	v_mfma_f32_16x16x32_bf16 v[122:125], v[148:151], v[210:213], v[122:125]
	v_mfma_f32_16x16x32_bf16 v[110:113], v[136:139], v[218:221], v[110:113]
	v_mfma_f32_16x16x32_bf16 v[106:109], v[148:151], v[218:221], v[106:109]
	v_mfma_f32_16x16x32_bf16 v[94:97], v[136:139], v[226:229], v[94:97]
	v_mfma_f32_16x16x32_bf16 v[90:93], v[148:151], v[226:229], v[90:93]
	v_mfma_f32_16x16x32_bf16 v[78:81], v[136:139], v[234:237], v[78:81]
	v_mfma_f32_16x16x32_bf16 v[74:77], v[148:151], v[234:237], v[74:77]
	v_mfma_f32_16x16x32_bf16 v[126:129], v[144:147], v[214:217], v[126:129]
	v_mfma_f32_16x16x32_bf16 v[122:125], v[152:155], v[214:217], v[122:125]
	v_mfma_f32_16x16x32_bf16 v[110:113], v[144:147], v[222:225], v[110:113]
	v_mfma_f32_16x16x32_bf16 v[106:109], v[152:155], v[222:225], v[106:109]
	v_mfma_f32_16x16x32_bf16 v[94:97], v[144:147], v[230:233], v[94:97]
	v_mfma_f32_16x16x32_bf16 v[90:93], v[152:155], v[230:233], v[90:93]
	v_mfma_f32_16x16x32_bf16 v[78:81], v[144:147], v[238:241], v[78:81]
	v_mfma_f32_16x16x32_bf16 v[74:77], v[152:155], v[238:241], v[74:77]
	s_setprio 0
	s_setprio 1
	v_mfma_f32_16x16x32_bf16 v[118:121], v[156:159], v[210:213], v[118:121]
	v_mfma_f32_16x16x32_bf16 v[114:117], v[192:195], v[210:213], v[114:117]
	v_mfma_f32_16x16x32_bf16 v[102:105], v[156:159], v[218:221], v[102:105]
	v_mfma_f32_16x16x32_bf16 v[98:101], v[192:195], v[218:221], v[98:101]
	v_mfma_f32_16x16x32_bf16 v[86:89], v[156:159], v[226:229], v[86:89]
	v_mfma_f32_16x16x32_bf16 v[82:85], v[192:195], v[226:229], v[82:85]
	v_mfma_f32_16x16x32_bf16 v[70:73], v[156:159], v[234:237], v[70:73]
	v_mfma_f32_16x16x32_bf16 v[66:69], v[192:195], v[234:237], v[66:69]
	v_mfma_f32_16x16x32_bf16 v[118:121], v[188:191], v[214:217], v[118:121]
	v_mfma_f32_16x16x32_bf16 v[114:117], v[196:199], v[214:217], v[114:117]
	v_mfma_f32_16x16x32_bf16 v[102:105], v[188:191], v[222:225], v[102:105]
	v_mfma_f32_16x16x32_bf16 v[98:101], v[196:199], v[222:225], v[98:101]
	v_mfma_f32_16x16x32_bf16 v[86:89], v[188:191], v[230:233], v[86:89]
	v_mfma_f32_16x16x32_bf16 v[82:85], v[196:199], v[230:233], v[82:85]
	v_mfma_f32_16x16x32_bf16 v[70:73], v[188:191], v[238:241], v[70:73]
	v_mfma_f32_16x16x32_bf16 v[66:69], v[196:199], v[238:241], v[66:69]
	s_setprio 0
	s_waitcnt vmcnt(8)
	s_barrier
	s_add_i32 s38, s38, s0
	v_lshl_add_u64 v[140:141], v[140:141], 0, s[56:57]
	s_mov_b32 m0, s38
	ds_read_b128 v[210:213], v143 offset:49152
	ds_read_b128 v[214:217], v143 offset:50176
	ds_read_b128 v[218:221], v143 offset:51200
	ds_read_b128 v[222:225], v143 offset:52224
	ds_read_b128 v[226:229], v143 offset:53248
	ds_read_b128 v[230:233], v143 offset:54272
	ds_read_b128 v[234:237], v143 offset:55296
	ds_read_b128 v[238:241], v143 offset:56320
	global_load_lds_dwordx4 v[140:141], off
	s_add_i32 m0, s38, 0x2000
	s_add_u32 s84, s84, 0x80080
	v_lshl_add_u64 v[140:141], v[160:161], 0, s[56:57]
	s_addc_u32 s85, s85, 0
	s_add_i32 s38, s39, s0
	global_load_lds_dwordx4 v[140:141], off
	v_lshl_add_u64 v[140:141], s[84:85], 0, v[166:167]
	s_mov_b32 m0, s38
	s_nop 0
	global_load_lds_dwordx4 v[140:141], off
	v_lshl_add_u64 v[140:141], s[84:85], 0, v[170:171]
	s_add_i32 m0, s38, 0x2000
	s_nop 0
	global_load_lds_dwordx4 v[140:141], off
	v_lshl_add_u64 v[140:141], v[242:243], 0, s[56:57]
	s_mov_b32 m0, s80
	s_nop 0
	global_load_lds_dwordx4 v[140:141], off
	v_lshl_add_u64 v[140:141], v[244:245], 0, s[56:57]
	s_mov_b32 m0, s81
	s_nop 0
	global_load_lds_dwordx4 v[140:141], off
	s_and_b64 vcc, exec, s[62:63]
	s_cbranch_vccz .Ldefer_b16_3
	s_waitcnt vmcnt(8)
.Ldefer_b16_3:
	s_waitcnt lgkmcnt(0)
	s_barrier
	s_setprio 1
	s_waitcnt lgkmcnt(0)
	v_mfma_f32_16x16x32_bf16 v[62:65], v[136:139], v[210:213], v[62:65]
	v_mfma_f32_16x16x32_bf16 v[58:61], v[148:151], v[210:213], v[58:61]
	v_mfma_f32_16x16x32_bf16 v[46:49], v[136:139], v[218:221], v[46:49]
	v_mfma_f32_16x16x32_bf16 v[42:45], v[148:151], v[218:221], v[42:45]
	v_mfma_f32_16x16x32_bf16 v[30:33], v[136:139], v[226:229], v[30:33]
	v_mfma_f32_16x16x32_bf16 v[26:29], v[148:151], v[226:229], v[26:29]
	v_mfma_f32_16x16x32_bf16 v[14:17], v[136:139], v[234:237], v[14:17]
	v_mfma_f32_16x16x32_bf16 v[10:13], v[148:151], v[234:237], v[10:13]
	v_mfma_f32_16x16x32_bf16 v[62:65], v[144:147], v[214:217], v[62:65]
	v_mfma_f32_16x16x32_bf16 v[58:61], v[152:155], v[214:217], v[58:61]
	v_mfma_f32_16x16x32_bf16 v[46:49], v[144:147], v[222:225], v[46:49]
	v_mfma_f32_16x16x32_bf16 v[42:45], v[152:155], v[222:225], v[42:45]
	v_mfma_f32_16x16x32_bf16 v[30:33], v[144:147], v[230:233], v[30:33]
	v_mfma_f32_16x16x32_bf16 v[26:29], v[152:155], v[230:233], v[26:29]
	v_mfma_f32_16x16x32_bf16 v[14:17], v[144:147], v[238:241], v[14:17]
	v_mfma_f32_16x16x32_bf16 v[10:13], v[152:155], v[238:241], v[10:13]
	s_setprio 0
	s_setprio 1
	v_mfma_f32_16x16x32_bf16 v[54:57], v[156:159], v[210:213], v[54:57]
	v_mfma_f32_16x16x32_bf16 v[50:53], v[192:195], v[210:213], v[50:53]
	v_mfma_f32_16x16x32_bf16 v[38:41], v[156:159], v[218:221], v[38:41]
	v_mfma_f32_16x16x32_bf16 v[34:37], v[192:195], v[218:221], v[34:37]
	v_mfma_f32_16x16x32_bf16 v[22:25], v[156:159], v[226:229], v[22:25]
	v_mfma_f32_16x16x32_bf16 v[18:21], v[192:195], v[226:229], v[18:21]
	v_mfma_f32_16x16x32_bf16 v[6:9], v[156:159], v[234:237], v[6:9]
	v_mfma_f32_16x16x32_bf16 v[2:5], v[192:195], v[234:237], v[2:5]
	v_mfma_f32_16x16x32_bf16 v[54:57], v[188:191], v[214:217], v[54:57]
	v_mfma_f32_16x16x32_bf16 v[50:53], v[196:199], v[214:217], v[50:53]
	v_mfma_f32_16x16x32_bf16 v[38:41], v[188:191], v[222:225], v[38:41]
	v_mfma_f32_16x16x32_bf16 v[34:37], v[196:199], v[222:225], v[34:37]
	v_mfma_f32_16x16x32_bf16 v[22:25], v[188:191], v[230:233], v[22:25]
	v_mfma_f32_16x16x32_bf16 v[18:21], v[196:199], v[230:233], v[18:21]
	v_mfma_f32_16x16x32_bf16 v[6:9], v[188:191], v[238:241], v[6:9]
	v_mfma_f32_16x16x32_bf16 v[2:5], v[196:199], v[238:241], v[2:5]
	s_setprio 0
	s_waitcnt vmcnt(8)
	s_barrier
	s_cmp_ge_i32 s34, s48
	s_mov_b32 s46, s34
	s_cbranch_scc1 .LBB0_398

; #define PG8_STAGE(bufoff, gbase, voff) do { _Pragma("unroll") for (int _i = 0; _i < 2; ++_i) \
;         __builtin_amdgcn_global_load_lds((const unsigned*)((const char*)(gbase) + (voff)[_i]), (PG8_LAS unsigned*)(lds + (bufoff) + ldsw + _i * 8192), 16, 0, 0); } while (0)
; #define PG8_LDA(dst, b, h) do { _Pragma("unroll") for (int m = 0; m < 4; ++m) _Pragma("unroll") for (int k = 0; k < 2; ++k) dst[m][k] = *(const PG8_LAS bf16x8*)(lds + PG8_SA(b, h) + aoff + m * 2048 + k * KOFF); } while (0)
; #define PG8_LDB(dst, b, h) do { _Pragma("unroll") for (int n = 0; n < 2; ++n) _Pragma("unroll") for (int k = 0; k < 2; ++k) dst[n][k] = *(const PG8_LAS bf16x8*)(lds + PG8_SB(b, h) + boff + n * 2048 + k * KOFF); } while (0)
; #define PG8_WAIT_V(n) asm volatile("s_waitcnt vmcnt(" #n ")" ::: "memory")
; #define PG8_WAIT_L(n) asm volatile("s_waitcnt lgkmcnt(" #n ")" ::: "memory")
; #define PG8_BAR __builtin_amdgcn_s_barrier()
; #define PG8_SCHED __builtin_amdgcn_sched_barrier(0)
; template <class Epi, class Sched, bool ALIGN_EPI = false, bool SP2 = false, bool F8 = false>
; __device__ __forceinline__ void gemm_phase(PG8_LAS unsigned char* lds, const Gemm g, const Sched& S, const Epi& E) {
;     ...
;             PG8_LDB(B0, 0, 0); PG8_LDB(B1, 0, 1); PG8_SCHED; PG8_LDA(At, 0, 0); PG8_STAGE(PG8_SA(1, 1), a1 + hstep, voffA);
;             PG8_WAIT_V(8); PG8_WAIT_L(0); PG8_BAR; PG8_MMA(0, 0, At, B0); PG8_MMA(0, 1, At, B1); PG8_BAR; PG8_SCHED;
;             PG8_LDA(At, 0, 1); PG8_STAGE(PG8_SB(0, 0), b2, voffB); PG8_STAGE(PG8_SB(0, 1), b2 + hstep, voffB); PG8_STAGE(PG8_SA(0, 0), a2, voffA);
;             PG8_WAIT_V(8); PG8_WAIT_L(0); PG8_BAR; PG8_MMA(1, 0, At, B0); PG8_MMA(1, 1, At, B1); PG8_BAR; PG8_SCHED;
.LBB0_652:
	s_or_b32 s34, s46, 1
	s_lshl_b64 vcc, s[34:35], 7
	s_add_i32 s34, s46, 2
	s_lshl_b64 s[88:89], s[34:35], 7
	s_add_u32 s46, s4, s88
	s_addc_u32 s38, s5, s89
	s_and_b64 s[86:87], s[84:85], exec
	s_cselect_b32 s87, s71, s38
	s_cselect_b32 s86, s70, s46
	s_add_u32 s38, s6, s88
	s_addc_u32 s39, s7, s89
	s_and_b64 s[84:85], s[84:85], exec
	s_cselect_b32 s85, s73, s39
	s_cselect_b32 s84, s72, s38
	s_add_i32 s88, 0, 0x10000
	s_add_i32 s46, 0, 0x14000
	v_add_u32_e32 v2, s88, v210
	v_add_u32_e32 v6, s46, v210
	ds_read_b128 v[26:29], v2
	ds_read_b128 v[30:33], v2 offset:16
	ds_read_b128 v[18:21], v2 offset:2048
	ds_read_b128 v[22:25], v2 offset:2064
	ds_read_b128 v[10:13], v6
	ds_read_b128 v[14:17], v6 offset:16
	s_waitcnt lgkmcnt(0)
	ds_read_b128 v[2:5], v6 offset:2048
	ds_read_b128 v[6:9], v6 offset:2064
	s_add_u32 vcc_lo, s67, vcc_lo
	s_addc_u32 vcc_hi, s69, vcc_hi
	v_lshl_add_u64 v[236:237], vcc, 0, v[176:177]
	s_add_i32 m0, s0, 0xc000
	ds_read_b128 v[192:195], v211
	ds_read_b128 v[196:199], v211 offset:16
	ds_read_b128 v[212:215], v211 offset:2048
	ds_read_b128 v[216:219], v211 offset:2064
	ds_read_b128 v[220:223], v211 offset:4096
	ds_read_b128 v[224:227], v211 offset:4112
	ds_read_b128 v[228:231], v211 offset:6144
	ds_read_b128 v[232:235], v211 offset:6160
	global_load_lds_dwordx4 v[236:237], off
	v_lshl_add_u64 v[236:237], vcc, 0, v[180:181]
	s_add_i32 m0, s0, 0xe000
	s_nop 0
	global_load_lds_dwordx4 v[236:237], off
	s_and_b64 vcc, exec, s[62:63]
	s_cbranch_vccz .Ldefer_f8_0
	s_waitcnt vmcnt(8)
.Ldefer_f8_0:
	s_waitcnt lgkmcnt(0)
	s_barrier
	s_setprio 1
	s_waitcnt lgkmcnt(0)
	v_mfma_scale_f32_16x16x128_f8f6f4 v[158:161], v[26:33], v[192:199], v[158:161], v207, v207 op_sel_hi:[0,0,0]
	v_mfma_scale_f32_16x16x128_f8f6f4 v[154:157], v[18:25], v[192:199], v[154:157], v207, v207 op_sel_hi:[0,0,0]
	v_mfma_scale_f32_16x16x128_f8f6f4 v[142:145], v[26:33], v[212:219], v[142:145], v207, v207 op_sel_hi:[0,0,0]
	v_mfma_scale_f32_16x16x128_f8f6f4 v[138:141], v[18:25], v[212:219], v[138:141], v207, v207 op_sel_hi:[0,0,0]
	v_mfma_scale_f32_16x16x128_f8f6f4 v[126:129], v[26:33], v[220:227], v[126:129], v207, v207 op_sel_hi:[0,0,0]
	v_mfma_scale_f32_16x16x128_f8f6f4 v[122:125], v[18:25], v[220:227], v[122:125], v207, v207 op_sel_hi:[0,0,0]
	v_mfma_scale_f32_16x16x128_f8f6f4 v[110:113], v[26:33], v[228:235], v[110:113], v207, v207 op_sel_hi:[0,0,0]
	v_mfma_scale_f32_16x16x128_f8f6f4 v[106:109], v[18:25], v[228:235], v[106:109], v207, v207 op_sel_hi:[0,0,0]
	s_setprio 0
	s_setprio 1
	v_mfma_scale_f32_16x16x128_f8f6f4 v[150:153], v[10:17], v[192:199], v[150:153], v207, v207 op_sel_hi:[0,0,0]
	v_mfma_scale_f32_16x16x128_f8f6f4 v[146:149], v[2:9], v[192:199], v[146:149], v207, v207 op_sel_hi:[0,0,0]
	v_mfma_scale_f32_16x16x128_f8f6f4 v[134:137], v[10:17], v[212:219], v[134:137], v207, v207 op_sel_hi:[0,0,0]
	v_mfma_scale_f32_16x16x128_f8f6f4 v[130:133], v[2:9], v[212:219], v[130:133], v207, v207 op_sel_hi:[0,0,0]
	v_mfma_scale_f32_16x16x128_f8f6f4 v[118:121], v[10:17], v[220:227], v[118:121], v207, v207 op_sel_hi:[0,0,0]
	v_mfma_scale_f32_16x16x128_f8f6f4 v[114:117], v[2:9], v[220:227], v[114:117], v207, v207 op_sel_hi:[0,0,0]
	v_mfma_scale_f32_16x16x128_f8f6f4 v[102:105], v[10:17], v[228:235], v[102:105], v207, v207 op_sel_hi:[0,0,0]
	v_mfma_scale_f32_16x16x128_f8f6f4 v[98:101], v[2:9], v[228:235], v[98:101], v207, v207 op_sel_hi:[0,0,0]
	s_setprio 0
	s_waitcnt vmcnt(8)
	s_barrier
	s_add_i32 s38, s88, s97
	v_lshl_add_u64 v[192:193], s[84:85], 0, v[178:179]
	s_mov_b32 m0, s38
	ds_read_b128 v[212:215], v211 offset:16384
	ds_read_b128 v[216:219], v211 offset:16400
	ds_read_b128 v[220:223], v211 offset:18432
	ds_read_b128 v[224:227], v211 offset:18448
	ds_read_b128 v[228:231], v211 offset:20480
	ds_read_b128 v[232:235], v211 offset:20496
	ds_read_b128 v[236:239], v211 offset:22528
	ds_read_b128 v[240:243], v211 offset:22544
	global_load_lds_dwordx4 v[192:193], off
	s_add_i32 m0, s38, 0x2000
	s_add_u32 s88, s84, 0x40000
	v_lshl_add_u64 v[194:195], s[84:85], 0, v[182:183]
	s_addc_u32 s89, s85, 0
	s_add_i32 s38, s46, s97
	global_load_lds_dwordx4 v[194:195], off
	v_lshl_add_u64 v[196:197], s[88:89], 0, v[178:179]
	s_mov_b32 m0, s38
	v_lshl_add_u64 v[198:199], s[86:87], 0, v[180:181]
	global_load_lds_dwordx4 v[196:197], off
	v_lshl_add_u64 v[196:197], s[88:89], 0, v[182:183]
	s_add_i32 m0, s38, 0x2000
	s_nop 0
	global_load_lds_dwordx4 v[196:197], off
	v_lshl_add_u64 v[196:197], s[86:87], 0, v[176:177]
	s_mov_b32 m0, s0
	s_nop 0
	global_load_lds_dwordx4 v[196:197], off
	s_mov_b32 m0, s1
	s_nop 0
	global_load_lds_dwordx4 v[198:199], off
	s_and_b64 vcc, exec, s[62:63]
	s_cbranch_vccz .Ldefer_f8_1
	s_waitcnt vmcnt(8)
; #define PG8_STAGE(bufoff, gbase, voff) do { _Pragma("unroll") for (int _i = 0; _i < 2; ++_i) \
;         __builtin_amdgcn_global_load_lds((const unsigned*)((const char*)(gbase) + (voff)[_i]), (PG8_LAS unsigned*)(lds + (bufoff) + ldsw + _i * 8192), 16, 0, 0); } while (0)
; #define PG8_LDA(dst, b, h) do { _Pragma("unroll") for (int m = 0; m < 4; ++m) _Pragma("unroll") for (int k = 0; k < 2; ++k) dst[m][k] = *(const PG8_LAS bf16x8*)(lds + PG8_SA(b, h) + aoff + m * 2048 + k * KOFF); } while (0)
; #define PG8_LDB(dst, b, h) do { _Pragma("unroll") for (int n = 0; n < 2; ++n) _Pragma("unroll") for (int k = 0; k < 2; ++k) dst[n][k] = *(const PG8_LAS bf16x8*)(lds + PG8_SB(b, h) + boff + n * 2048 + k * KOFF); } while (0)
; #define PG8_WAIT_V(n) asm volatile("s_waitcnt vmcnt(" #n ")" ::: "memory")
; #define PG8_WAIT_L(n) asm volatile("s_waitcnt lgkmcnt(" #n ")" ::: "memory")
; #define PG8_BAR __builtin_amdgcn_s_barrier()
; #define PG8_SCHED __builtin_amdgcn_sched_barrier(0)
; template <class Epi, class Sched, bool ALIGN_EPI = false, bool SP2 = false, bool F8 = false>
; __device__ __forceinline__ void gemm_phase(PG8_LAS unsigned char* lds, const Gemm g, const Sched& S, const Epi& E) {
;     ...
;             PG8_WAIT_V(8); PG8_WAIT_L(0); PG8_BAR; PG8_MMA(1, 0, At, B0); PG8_MMA(1, 1, At, B1); PG8_BAR; PG8_SCHED;
;             PG8_LDB(B0, 1, 0); PG8_LDB(B1, 1, 1); PG8_SCHED; PG8_LDA(At, 1, 0); PG8_STAGE(PG8_SA(0, 1), a2 + hstep, voffA);
.Ldefer_f8_1:
	s_waitcnt lgkmcnt(0)
	s_barrier
	s_setprio 1
	s_waitcnt lgkmcnt(0)
	v_mfma_scale_f32_16x16x128_f8f6f4 v[94:97], v[26:33], v[212:219], v[94:97], v207, v207 op_sel_hi:[0,0,0]
	v_mfma_scale_f32_16x16x128_f8f6f4 v[90:93], v[18:25], v[212:219], v[90:93], v207, v207 op_sel_hi:[0,0,0]
	v_mfma_scale_f32_16x16x128_f8f6f4 v[78:81], v[26:33], v[220:227], v[78:81], v207, v207 op_sel_hi:[0,0,0]
	v_mfma_scale_f32_16x16x128_f8f6f4 v[74:77], v[18:25], v[220:227], v[74:77], v207, v207 op_sel_hi:[0,0,0]
	v_mfma_scale_f32_16x16x128_f8f6f4 v[62:65], v[26:33], v[228:235], v[62:65], v207, v207 op_sel_hi:[0,0,0]
	v_mfma_scale_f32_16x16x128_f8f6f4 v[58:61], v[18:25], v[228:235], v[58:61], v207, v207 op_sel_hi:[0,0,0]
	v_mfma_scale_f32_16x16x128_f8f6f4 v[46:49], v[26:33], v[236:243], v[46:49], v207, v207 op_sel_hi:[0,0,0]
	v_mfma_scale_f32_16x16x128_f8f6f4 v[42:45], v[18:25], v[236:243], v[42:45], v207, v207 op_sel_hi:[0,0,0]
	s_setprio 0
	s_setprio 1
	v_mfma_scale_f32_16x16x128_f8f6f4 v[86:89], v[10:17], v[212:219], v[86:89], v207, v207 op_sel_hi:[0,0,0]
	v_mfma_scale_f32_16x16x128_f8f6f4 v[82:85], v[2:9], v[212:219], v[82:85], v207, v207 op_sel_hi:[0,0,0]
	v_mfma_scale_f32_16x16x128_f8f6f4 v[70:73], v[10:17], v[220:227], v[70:73], v207, v207 op_sel_hi:[0,0,0]
	v_mfma_scale_f32_16x16x128_f8f6f4 v[66:69], v[2:9], v[220:227], v[66:69], v207, v207 op_sel_hi:[0,0,0]
	v_mfma_scale_f32_16x16x128_f8f6f4 v[54:57], v[10:17], v[228:235], v[54:57], v207, v207 op_sel_hi:[0,0,0]
	v_mfma_scale_f32_16x16x128_f8f6f4 v[50:53], v[2:9], v[228:235], v[50:53], v207, v207 op_sel_hi:[0,0,0]
	v_mfma_scale_f32_16x16x128_f8f6f4 v[38:41], v[10:17], v[236:243], v[38:41], v207, v207 op_sel_hi:[0,0,0]
	v_mfma_scale_f32_16x16x128_f8f6f4 v[34:37], v[2:9], v[236:243], v[34:37], v207, v207 op_sel_hi:[0,0,0]
	s_setprio 0
	s_waitcnt vmcnt(8)
	s_barrier
	s_add_i32 s38, 0, 0x18000
	s_add_i32 s39, 0, 0x1c000
	v_add_u32_e32 v14, s38, v210
	v_add_u32_e32 v30, s39, v210
	ds_read_b128 v[2:5], v14
	ds_read_b128 v[6:9], v14 offset:16
	ds_read_b128 v[10:13], v14 offset:2048
	ds_read_b128 v[14:17], v14 offset:2064
	ds_read_b128 v[18:21], v30
	ds_read_b128 v[22:25], v30 offset:16
	ds_read_b128 v[26:29], v30 offset:2048
	ds_read_b128 v[30:33], v30 offset:2064
	s_add_u32 s86, s86, 0x40000
	s_addc_u32 s87, s87, 0
	s_mov_b32 m0, s36
	v_lshl_add_u64 v[244:245], s[86:87], 0, v[176:177]
	ds_read_b128 v[212:215], v211 offset:32768
	ds_read_b128 v[216:219], v211 offset:32784
	ds_read_b128 v[220:223], v211 offset:34816
	ds_read_b128 v[224:227], v211 offset:34832
	ds_read_b128 v[228:231], v211 offset:36864
	ds_read_b128 v[232:235], v211 offset:36880
	ds_read_b128 v[236:239], v211 offset:38912
	ds_read_b128 v[240:243], v211 offset:38928
	global_load_lds_dwordx4 v[244:245], off
	v_lshl_add_u64 v[244:245], s[86:87], 0, v[180:181]
	s_mov_b32 m0, s74
	s_nop 0
	global_load_lds_dwordx4 v[244:245], off
	s_and_b64 vcc, exec, s[62:63]
	s_cbranch_vccz .Ldefer_f8_2
	s_waitcnt vmcnt(8)
; #define PG8_STAGE(bufoff, gbase, voff) do { _Pragma("unroll") for (int _i = 0; _i < 2; ++_i) \
;         __builtin_amdgcn_global_load_lds((const unsigned*)((const char*)(gbase) + (voff)[_i]), (PG8_LAS unsigned*)(lds + (bufoff) + ldsw + _i * 8192), 16, 0, 0); } while (0)
; #define PG8_LDA(dst, b, h) do { _Pragma("unroll") for (int m = 0; m < 4; ++m) _Pragma("unroll") for (int k = 0; k < 2; ++k) dst[m][k] = *(const PG8_LAS bf16x8*)(lds + PG8_SA(b, h) + aoff + m * 2048 + k * KOFF); } while (0)
; #define PG8_WAIT_V(n) asm volatile("s_waitcnt vmcnt(" #n ")" ::: "memory")
; #define PG8_WAIT_L(n) asm volatile("s_waitcnt lgkmcnt(" #n ")" ::: "memory")
; #define PG8_BAR __builtin_amdgcn_s_barrier()
; #define PG8_SCHED __builtin_amdgcn_sched_barrier(0)
; template <class Epi, class Sched, bool ALIGN_EPI = false, bool SP2 = false, bool F8 = false>
; __device__ __forceinline__ void gemm_phase(PG8_LAS unsigned char* lds, const Gemm g, const Sched& S, const Epi& E) {
;     ...
;             PG8_WAIT_V(8); PG8_WAIT_L(0); PG8_BAR; PG8_MMA(0, 0, At, B0); PG8_MMA(0, 1, At, B1); PG8_BAR; PG8_SCHED;
;             PG8_LDA(At, 1, 1); PG8_STAGE(PG8_SB(1, 0), b3, voffB); PG8_STAGE(PG8_SB(1, 1), b3 + hstep, voffB); PG8_STAGE(PG8_SA(1, 0), a3, voffA);
;             PG8_WAIT_V(8); PG8_WAIT_L(0); PG8_BAR; PG8_MMA(1, 0, At, B0); PG8_MMA(1, 1, At, B1); PG8_BAR; PG8_SCHED;
.Ldefer_f8_2:
	s_waitcnt lgkmcnt(0)
	s_barrier
	s_setprio 1
	s_waitcnt lgkmcnt(0)
	v_mfma_scale_f32_16x16x128_f8f6f4 v[158:161], v[2:9], v[212:219], v[158:161], v207, v207 op_sel_hi:[0,0,0]
	v_mfma_scale_f32_16x16x128_f8f6f4 v[154:157], v[10:17], v[212:219], v[154:157], v207, v207 op_sel_hi:[0,0,0]
	v_mfma_scale_f32_16x16x128_f8f6f4 v[142:145], v[2:9], v[220:227], v[142:145], v207, v207 op_sel_hi:[0,0,0]
	v_mfma_scale_f32_16x16x128_f8f6f4 v[138:141], v[10:17], v[220:227], v[138:141], v207, v207 op_sel_hi:[0,0,0]
	v_mfma_scale_f32_16x16x128_f8f6f4 v[126:129], v[2:9], v[228:235], v[126:129], v207, v207 op_sel_hi:[0,0,0]
	v_mfma_scale_f32_16x16x128_f8f6f4 v[122:125], v[10:17], v[228:235], v[122:125], v207, v207 op_sel_hi:[0,0,0]
	v_mfma_scale_f32_16x16x128_f8f6f4 v[110:113], v[2:9], v[236:243], v[110:113], v207, v207 op_sel_hi:[0,0,0]
	v_mfma_scale_f32_16x16x128_f8f6f4 v[106:109], v[10:17], v[236:243], v[106:109], v207, v207 op_sel_hi:[0,0,0]
	s_setprio 0
	s_setprio 1
	v_mfma_scale_f32_16x16x128_f8f6f4 v[150:153], v[18:25], v[212:219], v[150:153], v207, v207 op_sel_hi:[0,0,0]
	v_mfma_scale_f32_16x16x128_f8f6f4 v[146:149], v[26:33], v[212:219], v[146:149], v207, v207 op_sel_hi:[0,0,0]
	v_mfma_scale_f32_16x16x128_f8f6f4 v[134:137], v[18:25], v[220:227], v[134:137], v207, v207 op_sel_hi:[0,0,0]
	v_mfma_scale_f32_16x16x128_f8f6f4 v[130:133], v[26:33], v[220:227], v[130:133], v207, v207 op_sel_hi:[0,0,0]
	v_mfma_scale_f32_16x16x128_f8f6f4 v[118:121], v[18:25], v[228:235], v[118:121], v207, v207 op_sel_hi:[0,0,0]
	v_mfma_scale_f32_16x16x128_f8f6f4 v[114:117], v[26:33], v[228:235], v[114:117], v207, v207 op_sel_hi:[0,0,0]
	v_mfma_scale_f32_16x16x128_f8f6f4 v[102:105], v[18:25], v[236:243], v[102:105], v207, v207 op_sel_hi:[0,0,0]
	v_mfma_scale_f32_16x16x128_f8f6f4 v[98:101], v[26:33], v[236:243], v[98:101], v207, v207 op_sel_hi:[0,0,0]
	s_setprio 0
	s_waitcnt vmcnt(8)
	s_barrier
	s_add_i32 s38, s38, s97
	v_lshl_add_u64 v[192:193], v[192:193], 0, s[56:57]
	s_mov_b32 m0, s38
	ds_read_b128 v[212:215], v211 offset:49152
	ds_read_b128 v[216:219], v211 offset:49168
	ds_read_b128 v[220:223], v211 offset:51200
	ds_read_b128 v[224:227], v211 offset:51216
	ds_read_b128 v[228:231], v211 offset:53248
	ds_read_b128 v[232:235], v211 offset:53264
	ds_read_b128 v[236:239], v211 offset:55296
	ds_read_b128 v[240:243], v211 offset:55312
	global_load_lds_dwordx4 v[192:193], off
	s_add_i32 m0, s38, 0x2000
	s_add_u32 s84, s84, 0x40080
	v_lshl_add_u64 v[192:193], v[194:195], 0, s[56:57]
	s_addc_u32 s85, s85, 0
	s_add_i32 s38, s39, s97
	global_load_lds_dwordx4 v[192:193], off
	v_lshl_add_u64 v[192:193], s[84:85], 0, v[178:179]
	s_mov_b32 m0, s38
	s_nop 0
	global_load_lds_dwordx4 v[192:193], off
	v_lshl_add_u64 v[192:193], s[84:85], 0, v[182:183]
	s_add_i32 m0, s38, 0x2000
	s_nop 0
	global_load_lds_dwordx4 v[192:193], off
	v_lshl_add_u64 v[192:193], v[196:197], 0, s[56:57]
	s_mov_b32 m0, s75
	s_nop 0
	global_load_lds_dwordx4 v[192:193], off
	v_lshl_add_u64 v[192:193], v[198:199], 0, s[56:57]
	s_mov_b32 m0, s80
	s_nop 0
	global_load_lds_dwordx4 v[192:193], off
	s_and_b64 vcc, exec, s[62:63]
	s_cbranch_vccz .Ldefer_f8_3
	s_waitcnt vmcnt(8)
.Ldefer_f8_3:
	s_waitcnt lgkmcnt(0)
	s_barrier
	s_setprio 1
	s_waitcnt lgkmcnt(0)
	v_mfma_scale_f32_16x16x128_f8f6f4 v[94:97], v[2:9], v[212:219], v[94:97], v207, v207 op_sel_hi:[0,0,0]
	v_mfma_scale_f32_16x16x128_f8f6f4 v[90:93], v[10:17], v[212:219], v[90:93], v207, v207 op_sel_hi:[0,0,0]
	v_mfma_scale_f32_16x16x128_f8f6f4 v[78:81], v[2:9], v[220:227], v[78:81], v207, v207 op_sel_hi:[0,0,0]
	v_mfma_scale_f32_16x16x128_f8f6f4 v[74:77], v[10:17], v[220:227], v[74:77], v207, v207 op_sel_hi:[0,0,0]
	v_mfma_scale_f32_16x16x128_f8f6f4 v[62:65], v[2:9], v[228:235], v[62:65], v207, v207 op_sel_hi:[0,0,0]
	v_mfma_scale_f32_16x16x128_f8f6f4 v[58:61], v[10:17], v[228:235], v[58:61], v207, v207 op_sel_hi:[0,0,0]
	v_mfma_scale_f32_16x16x128_f8f6f4 v[46:49], v[2:9], v[236:243], v[46:49], v207, v207 op_sel_hi:[0,0,0]
	v_mfma_scale_f32_16x16x128_f8f6f4 v[42:45], v[10:17], v[236:243], v[42:45], v207, v207 op_sel_hi:[0,0,0]
	s_setprio 0
	s_setprio 1
	v_mfma_scale_f32_16x16x128_f8f6f4 v[86:89], v[18:25], v[212:219], v[86:89], v207, v207 op_sel_hi:[0,0,0]
	v_mfma_scale_f32_16x16x128_f8f6f4 v[82:85], v[26:33], v[212:219], v[82:85], v207, v207 op_sel_hi:[0,0,0]
	v_mfma_scale_f32_16x16x128_f8f6f4 v[70:73], v[18:25], v[220:227], v[70:73], v207, v207 op_sel_hi:[0,0,0]
	v_mfma_scale_f32_16x16x128_f8f6f4 v[66:69], v[26:33], v[220:227], v[66:69], v207, v207 op_sel_hi:[0,0,0]
	v_mfma_scale_f32_16x16x128_f8f6f4 v[54:57], v[18:25], v[228:235], v[54:57], v207, v207 op_sel_hi:[0,0,0]
	v_mfma_scale_f32_16x16x128_f8f6f4 v[50:53], v[26:33], v[228:235], v[50:53], v207, v207 op_sel_hi:[0,0,0]
	v_mfma_scale_f32_16x16x128_f8f6f4 v[38:41], v[18:25], v[236:243], v[38:41], v207, v207 op_sel_hi:[0,0,0]
	v_mfma_scale_f32_16x16x128_f8f6f4 v[34:37], v[26:33], v[236:243], v[34:37], v207, v207 op_sel_hi:[0,0,0]
	s_setprio 0
	s_waitcnt vmcnt(8)
	s_barrier
	s_cmp_ge_i32 s34, s48
	s_mov_b32 s46, s34
	s_cbranch_scc1 .LBB0_663

; #define PG8_STAGE(bufoff, gbase, voff) do { _Pragma("unroll") for (int _i = 0; _i < 2; ++_i) \
;         __builtin_amdgcn_global_load_lds((const unsigned*)((const char*)(gbase) + (voff)[_i]), (PG8_LAS unsigned*)(lds + (bufoff) + ldsw + _i * 8192), 16, 0, 0); } while (0)
; #define PG8_LDA(dst, b, h) do { _Pragma("unroll") for (int m = 0; m < 4; ++m) _Pragma("unroll") for (int k = 0; k < 2; ++k) dst[m][k] = *(const PG8_LAS bf16x8*)(lds + PG8_SA(b, h) + aoff + m * 2048 + k * KOFF); } while (0)
; #define PG8_LDB(dst, b, h) do { _Pragma("unroll") for (int n = 0; n < 2; ++n) _Pragma("unroll") for (int k = 0; k < 2; ++k) dst[n][k] = *(const PG8_LAS bf16x8*)(lds + PG8_SB(b, h) + boff + n * 2048 + k * KOFF); } while (0)
; #define PG8_WAIT_V(n) asm volatile("s_waitcnt vmcnt(" #n ")" ::: "memory")
; #define PG8_WAIT_L(n) asm volatile("s_waitcnt lgkmcnt(" #n ")" ::: "memory")
; #define PG8_BAR __builtin_amdgcn_s_barrier()
; #define PG8_SCHED __builtin_amdgcn_sched_barrier(0)
; template <class Epi, class Sched, bool ALIGN_EPI = false, bool SP2 = false, bool F8 = false>
; __device__ __forceinline__ void gemm_phase(PG8_LAS unsigned char* lds, const Gemm g, const Sched& S, const Epi& E) {
;     ...
;             PG8_LDB(B0, 0, 0); PG8_LDB(B1, 0, 1); PG8_SCHED; PG8_LDA(At, 0, 0); PG8_STAGE(PG8_SA(1, 1), a1 + hstep, voffA);
;             PG8_WAIT_V(8); PG8_WAIT_L(0); PG8_BAR; PG8_MMA(0, 0, At, B0); PG8_MMA(0, 1, At, B1); PG8_BAR; PG8_SCHED;
;             PG8_LDA(At, 0, 1); PG8_STAGE(PG8_SB(0, 0), b2, voffB); PG8_STAGE(PG8_SB(0, 1), b2 + hstep, voffB); PG8_STAGE(PG8_SA(0, 0), a2, voffA);
;             PG8_WAIT_V(8); PG8_WAIT_L(0); PG8_BAR; PG8_MMA(1, 0, At, B0); PG8_MMA(1, 1, At, B1); PG8_BAR; PG8_SCHED;
.LBB0_1092:
	v_add_u32_e32 v14, s72, v163
	v_add_u32_e32 v30, s73, v163
	ds_read_b128 v[2:5], v14
	ds_read_b128 v[6:9], v14 offset:16
	ds_read_b128 v[10:13], v14 offset:2048
	ds_read_b128 v[14:17], v14 offset:2064
	ds_read_b128 v[18:21], v30
	ds_read_b128 v[22:25], v30 offset:16
	ds_read_b128 v[26:29], v30 offset:2048
	ds_read_b128 v[30:33], v30 offset:2064
	s_add_u32 s50, s40, s48
	s_addc_u32 s51, s41, s49
	s_add_u32 s79, s38, s48
	s_addc_u32 s80, s39, s49
	s_cmp_eq_u32 s76, s35
	s_cselect_b32 s53, s9, s51
	s_cselect_b32 s52, s11, s50
	s_cselect_b32 s51, s27, s80
	s_cselect_b32 s50, s31, s79
	v_lshl_add_u64 v[212:213], s[40:41], 0, v[176:177]
	s_add_i32 m0, s62, 0xc000
	ds_read_b128 v[178:181], v186
	ds_read_b128 v[182:185], v186 offset:16
	ds_read_b128 v[188:191], v186 offset:2048
	ds_read_b128 v[192:195], v186 offset:2064
	ds_read_b128 v[196:199], v186 offset:4096
	ds_read_b128 v[200:203], v186 offset:4112
	ds_read_b128 v[204:207], v186 offset:6144
	ds_read_b128 v[208:211], v186 offset:6160
	global_load_lds_dwordx4 v[212:213], off
	v_lshl_add_u64 v[212:213], s[40:41], 0, v[174:175]
	s_add_i32 m0, s62, 0xe000
	s_nop 0
	global_load_lds_dwordx4 v[212:213], off
	s_and_b64 vcc, exec, s[16:17]
	s_cbranch_vccz .Ldefer_g2_0
	s_waitcnt vmcnt(8)
.Ldefer_g2_0:
	s_waitcnt lgkmcnt(0)
	s_barrier
	s_setprio 1
	s_waitcnt lgkmcnt(0)
	v_mfma_scale_f32_16x16x128_f8f6f4 v[158:161], v[2:9], v[178:185], v[158:161], v187, v187 op_sel_hi:[0,0,0]
	v_mfma_scale_f32_16x16x128_f8f6f4 v[150:153], v[10:17], v[178:185], v[150:153], v187, v187 op_sel_hi:[0,0,0]
	v_mfma_scale_f32_16x16x128_f8f6f4 v[142:145], v[2:9], v[188:195], v[142:145], v187, v187 op_sel_hi:[0,0,0]
	v_mfma_scale_f32_16x16x128_f8f6f4 v[134:137], v[10:17], v[188:195], v[134:137], v187, v187 op_sel_hi:[0,0,0]
	v_mfma_scale_f32_16x16x128_f8f6f4 v[110:113], v[2:9], v[196:203], v[110:113], v187, v187 op_sel_hi:[0,0,0]
	v_mfma_scale_f32_16x16x128_f8f6f4 v[102:105], v[10:17], v[196:203], v[102:105], v187, v187 op_sel_hi:[0,0,0]
	v_mfma_scale_f32_16x16x128_f8f6f4 v[70:73], v[2:9], v[204:211], v[70:73], v187, v187 op_sel_hi:[0,0,0]
	v_mfma_scale_f32_16x16x128_f8f6f4 v[54:57], v[10:17], v[204:211], v[54:57], v187, v187 op_sel_hi:[0,0,0]
	s_setprio 0
	s_setprio 1
	v_mfma_scale_f32_16x16x128_f8f6f4 v[154:157], v[18:25], v[178:185], v[154:157], v187, v187 op_sel_hi:[0,0,0]
	v_mfma_scale_f32_16x16x128_f8f6f4 v[146:149], v[26:33], v[178:185], v[146:149], v187, v187 op_sel_hi:[0,0,0]
	v_mfma_scale_f32_16x16x128_f8f6f4 v[138:141], v[18:25], v[188:195], v[138:141], v187, v187 op_sel_hi:[0,0,0]
	v_mfma_scale_f32_16x16x128_f8f6f4 v[130:133], v[26:33], v[188:195], v[130:133], v187, v187 op_sel_hi:[0,0,0]
	v_mfma_scale_f32_16x16x128_f8f6f4 v[106:109], v[18:25], v[196:203], v[106:109], v187, v187 op_sel_hi:[0,0,0]
	v_mfma_scale_f32_16x16x128_f8f6f4 v[98:101], v[26:33], v[196:203], v[98:101], v187, v187 op_sel_hi:[0,0,0]
	v_mfma_scale_f32_16x16x128_f8f6f4 v[58:61], v[18:25], v[204:211], v[58:61], v187, v187 op_sel_hi:[0,0,0]
	v_mfma_scale_f32_16x16x128_f8f6f4 v[50:53], v[26:33], v[204:211], v[50:53], v187, v187 op_sel_hi:[0,0,0]
	s_setprio 0
	s_waitcnt vmcnt(8)
	s_barrier
	s_add_i32 s79, s72, s61
	v_lshl_add_u64 v[178:179], s[50:51], 0, v[164:165]
	s_mov_b32 m0, s79
	ds_read_b128 v[188:191], v186 offset:16384
	ds_read_b128 v[192:195], v186 offset:16400
	ds_read_b128 v[196:199], v186 offset:18432
	ds_read_b128 v[200:203], v186 offset:18448
	ds_read_b128 v[204:207], v186 offset:20480
	ds_read_b128 v[208:211], v186 offset:20496
	ds_read_b128 v[212:215], v186 offset:22528
	ds_read_b128 v[216:219], v186 offset:22544
	global_load_lds_dwordx4 v[178:179], off
	s_add_i32 m0, s79, 0x2000
	s_add_u32 s80, s50, 0x40000
	v_lshl_add_u64 v[180:181], s[50:51], 0, v[166:167]
	s_addc_u32 s81, s51, 0
	s_add_i32 s79, s73, s61
	global_load_lds_dwordx4 v[180:181], off
	v_lshl_add_u64 v[182:183], s[80:81], 0, v[164:165]
	s_mov_b32 m0, s79
	v_lshl_add_u64 v[184:185], s[52:53], 0, v[166:167]
	global_load_lds_dwordx4 v[182:183], off
	v_lshl_add_u64 v[182:183], s[80:81], 0, v[166:167]
	s_add_i32 m0, s79, 0x2000
	s_nop 0
	global_load_lds_dwordx4 v[182:183], off
	v_lshl_add_u64 v[182:183], s[52:53], 0, v[164:165]
	s_mov_b32 m0, s62
	s_nop 0
	global_load_lds_dwordx4 v[182:183], off
	s_mov_b32 m0, s63
	s_nop 0
	global_load_lds_dwordx4 v[184:185], off
	s_and_b64 vcc, exec, s[16:17]
	s_cbranch_vccz .Ldefer_g2_1
	s_waitcnt vmcnt(8)
; #define PG8_STAGE(bufoff, gbase, voff) do { _Pragma("unroll") for (int _i = 0; _i < 2; ++_i) \
;         __builtin_amdgcn_global_load_lds((const unsigned*)((const char*)(gbase) + (voff)[_i]), (PG8_LAS unsigned*)(lds + (bufoff) + ldsw + _i * 8192), 16, 0, 0); } while (0)
; #define PG8_LDA(dst, b, h) do { _Pragma("unroll") for (int m = 0; m < 4; ++m) _Pragma("unroll") for (int k = 0; k < 2; ++k) dst[m][k] = *(const PG8_LAS bf16x8*)(lds + PG8_SA(b, h) + aoff + m * 2048 + k * KOFF); } while (0)
; #define PG8_LDB(dst, b, h) do { _Pragma("unroll") for (int n = 0; n < 2; ++n) _Pragma("unroll") for (int k = 0; k < 2; ++k) dst[n][k] = *(const PG8_LAS bf16x8*)(lds + PG8_SB(b, h) + boff + n * 2048 + k * KOFF); } while (0)
; #define PG8_WAIT_V(n) asm volatile("s_waitcnt vmcnt(" #n ")" ::: "memory")
; #define PG8_WAIT_L(n) asm volatile("s_waitcnt lgkmcnt(" #n ")" ::: "memory")
; #define PG8_BAR __builtin_amdgcn_s_barrier()
; #define PG8_SCHED __builtin_amdgcn_sched_barrier(0)
; template <class Epi, class Sched, bool ALIGN_EPI = false, bool SP2 = false, bool F8 = false>
; __device__ __forceinline__ void gemm_phase(PG8_LAS unsigned char* lds, const Gemm g, const Sched& S, const Epi& E) {
;     ...
;             PG8_WAIT_V(8); PG8_WAIT_L(0); PG8_BAR; PG8_MMA(1, 0, At, B0); PG8_MMA(1, 1, At, B1); PG8_BAR; PG8_SCHED;
;             PG8_LDB(B0, 1, 0); PG8_LDB(B1, 1, 1); PG8_SCHED; PG8_LDA(At, 1, 0); PG8_STAGE(PG8_SA(0, 1), a2 + hstep, voffA);
.Ldefer_g2_1:
	s_waitcnt lgkmcnt(0)
	s_barrier
	s_setprio 1
	s_waitcnt lgkmcnt(0)
	v_mfma_scale_f32_16x16x128_f8f6f4 v[118:121], v[2:9], v[188:195], v[118:121], v187, v187 op_sel_hi:[0,0,0]
	v_mfma_scale_f32_16x16x128_f8f6f4 v[114:117], v[10:17], v[188:195], v[114:117], v187, v187 op_sel_hi:[0,0,0]
	v_mfma_scale_f32_16x16x128_f8f6f4 v[86:89], v[2:9], v[196:203], v[86:89], v187, v187 op_sel_hi:[0,0,0]
	v_mfma_scale_f32_16x16x128_f8f6f4 v[82:85], v[10:17], v[196:203], v[82:85], v187, v187 op_sel_hi:[0,0,0]
	v_mfma_scale_f32_16x16x128_f8f6f4 v[66:69], v[2:9], v[204:211], v[66:69], v187, v187 op_sel_hi:[0,0,0]
	v_mfma_scale_f32_16x16x128_f8f6f4 v[62:65], v[10:17], v[204:211], v[62:65], v187, v187 op_sel_hi:[0,0,0]
	v_mfma_scale_f32_16x16x128_f8f6f4 v[42:45], v[2:9], v[212:219], v[42:45], v187, v187 op_sel_hi:[0,0,0]
	v_mfma_scale_f32_16x16x128_f8f6f4 v[38:41], v[10:17], v[212:219], v[38:41], v187, v187 op_sel_hi:[0,0,0]
	s_setprio 0
	s_setprio 1
	v_mfma_scale_f32_16x16x128_f8f6f4 v[126:129], v[18:25], v[188:195], v[126:129], v187, v187 op_sel_hi:[0,0,0]
	v_mfma_scale_f32_16x16x128_f8f6f4 v[122:125], v[26:33], v[188:195], v[122:125], v187, v187 op_sel_hi:[0,0,0]
	v_mfma_scale_f32_16x16x128_f8f6f4 v[94:97], v[18:25], v[196:203], v[94:97], v187, v187 op_sel_hi:[0,0,0]
	v_mfma_scale_f32_16x16x128_f8f6f4 v[90:93], v[26:33], v[196:203], v[90:93], v187, v187 op_sel_hi:[0,0,0]
	v_mfma_scale_f32_16x16x128_f8f6f4 v[78:81], v[18:25], v[204:211], v[78:81], v187, v187 op_sel_hi:[0,0,0]
	v_mfma_scale_f32_16x16x128_f8f6f4 v[74:77], v[26:33], v[204:211], v[74:77], v187, v187 op_sel_hi:[0,0,0]
	v_mfma_scale_f32_16x16x128_f8f6f4 v[46:49], v[18:25], v[212:219], v[46:49], v187, v187 op_sel_hi:[0,0,0]
	v_mfma_scale_f32_16x16x128_f8f6f4 v[34:37], v[26:33], v[212:219], v[34:37], v187, v187 op_sel_hi:[0,0,0]
	s_setprio 0
	s_waitcnt vmcnt(8)
	s_barrier
	s_add_i32 s79, 0, 0x18000
	s_add_i32 s80, 0, 0x1c000
	v_add_u32_e32 v2, s79, v163
	v_add_u32_e32 v6, s80, v163
	ds_read_b128 v[26:29], v2
	ds_read_b128 v[30:33], v2 offset:16
	ds_read_b128 v[18:21], v2 offset:2048
	ds_read_b128 v[22:25], v2 offset:2064
	ds_read_b128 v[10:13], v6
	ds_read_b128 v[14:17], v6 offset:16
	ds_read_b128 v[2:5], v6 offset:2048
	ds_read_b128 v[6:9], v6 offset:2064
	s_add_u32 s52, s52, 0x40000
	s_addc_u32 s53, s53, 0
	s_mov_b32 m0, s64
	v_lshl_add_u64 v[220:221], s[52:53], 0, v[164:165]
	ds_read_b128 v[188:191], v186 offset:32768
	ds_read_b128 v[192:195], v186 offset:32784
	ds_read_b128 v[196:199], v186 offset:34816
	ds_read_b128 v[200:203], v186 offset:34832
	ds_read_b128 v[204:207], v186 offset:36864
	ds_read_b128 v[208:211], v186 offset:36880
	ds_read_b128 v[212:215], v186 offset:38912
	ds_read_b128 v[216:219], v186 offset:38928
	global_load_lds_dwordx4 v[220:221], off
	v_lshl_add_u64 v[220:221], s[52:53], 0, v[166:167]
	s_mov_b32 m0, s65
	s_nop 0
	global_load_lds_dwordx4 v[220:221], off
	s_and_b64 vcc, exec, s[16:17]
	s_cbranch_vccz .Ldefer_g2_2
	s_waitcnt vmcnt(8)
; #define PG8_STAGE(bufoff, gbase, voff) do { _Pragma("unroll") for (int _i = 0; _i < 2; ++_i) \
;         __builtin_amdgcn_global_load_lds((const unsigned*)((const char*)(gbase) + (voff)[_i]), (PG8_LAS unsigned*)(lds + (bufoff) + ldsw + _i * 8192), 16, 0, 0); } while (0)
; #define PG8_LDA(dst, b, h) do { _Pragma("unroll") for (int m = 0; m < 4; ++m) _Pragma("unroll") for (int k = 0; k < 2; ++k) dst[m][k] = *(const PG8_LAS bf16x8*)(lds + PG8_SA(b, h) + aoff + m * 2048 + k * KOFF); } while (0)
; #define PG8_WAIT_V(n) asm volatile("s_waitcnt vmcnt(" #n ")" ::: "memory")
; #define PG8_WAIT_L(n) asm volatile("s_waitcnt lgkmcnt(" #n ")" ::: "memory")
; #define PG8_BAR __builtin_amdgcn_s_barrier()
; #define PG8_SCHED __builtin_amdgcn_sched_barrier(0)
; template <class Epi, class Sched, bool ALIGN_EPI = false, bool SP2 = false, bool F8 = false>
; __device__ __forceinline__ void gemm_phase(PG8_LAS unsigned char* lds, const Gemm g, const Sched& S, const Epi& E) {
;     ...
;             PG8_WAIT_V(8); PG8_WAIT_L(0); PG8_BAR; PG8_MMA(0, 0, At, B0); PG8_MMA(0, 1, At, B1); PG8_BAR; PG8_SCHED;
;             PG8_LDA(At, 1, 1); PG8_STAGE(PG8_SB(1, 0), b3, voffB); PG8_STAGE(PG8_SB(1, 1), b3 + hstep, voffB); PG8_STAGE(PG8_SA(1, 0), a3, voffA);
;             PG8_WAIT_V(8); PG8_WAIT_L(0); PG8_BAR; PG8_MMA(1, 0, At, B0); PG8_MMA(1, 1, At, B1); PG8_BAR; PG8_SCHED;
;     ...
;         if constexpr (F8) asm volatile("s_nop 15\n\ts_nop 15" ::: "memory");
;         if constexpr (ALIGN_EPI) { if (wr == 0) PG8_BAR; }
.Ldefer_g2_2:
	s_waitcnt lgkmcnt(0)
	s_barrier
	s_setprio 1
	s_waitcnt lgkmcnt(0)
	v_mfma_scale_f32_16x16x128_f8f6f4 v[158:161], v[26:33], v[188:195], v[158:161], v187, v187 op_sel_hi:[0,0,0]
	v_mfma_scale_f32_16x16x128_f8f6f4 v[150:153], v[18:25], v[188:195], v[150:153], v187, v187 op_sel_hi:[0,0,0]
	v_mfma_scale_f32_16x16x128_f8f6f4 v[142:145], v[26:33], v[196:203], v[142:145], v187, v187 op_sel_hi:[0,0,0]
	v_mfma_scale_f32_16x16x128_f8f6f4 v[134:137], v[18:25], v[196:203], v[134:137], v187, v187 op_sel_hi:[0,0,0]
	v_mfma_scale_f32_16x16x128_f8f6f4 v[110:113], v[26:33], v[204:211], v[110:113], v187, v187 op_sel_hi:[0,0,0]
	v_mfma_scale_f32_16x16x128_f8f6f4 v[102:105], v[18:25], v[204:211], v[102:105], v187, v187 op_sel_hi:[0,0,0]
	v_mfma_scale_f32_16x16x128_f8f6f4 v[70:73], v[26:33], v[212:219], v[70:73], v187, v187 op_sel_hi:[0,0,0]
	v_mfma_scale_f32_16x16x128_f8f6f4 v[54:57], v[18:25], v[212:219], v[54:57], v187, v187 op_sel_hi:[0,0,0]
	s_setprio 0
	s_setprio 1
	v_mfma_scale_f32_16x16x128_f8f6f4 v[154:157], v[10:17], v[188:195], v[154:157], v187, v187 op_sel_hi:[0,0,0]
	v_mfma_scale_f32_16x16x128_f8f6f4 v[146:149], v[2:9], v[188:195], v[146:149], v187, v187 op_sel_hi:[0,0,0]
	v_mfma_scale_f32_16x16x128_f8f6f4 v[138:141], v[10:17], v[196:203], v[138:141], v187, v187 op_sel_hi:[0,0,0]
	v_mfma_scale_f32_16x16x128_f8f6f4 v[130:133], v[2:9], v[196:203], v[130:133], v187, v187 op_sel_hi:[0,0,0]
	v_mfma_scale_f32_16x16x128_f8f6f4 v[106:109], v[10:17], v[204:211], v[106:109], v187, v187 op_sel_hi:[0,0,0]
	v_mfma_scale_f32_16x16x128_f8f6f4 v[98:101], v[2:9], v[204:211], v[98:101], v187, v187 op_sel_hi:[0,0,0]
	v_mfma_scale_f32_16x16x128_f8f6f4 v[58:61], v[10:17], v[212:219], v[58:61], v187, v187 op_sel_hi:[0,0,0]
	v_mfma_scale_f32_16x16x128_f8f6f4 v[50:53], v[2:9], v[212:219], v[50:53], v187, v187 op_sel_hi:[0,0,0]
	s_setprio 0
	s_waitcnt vmcnt(8)
	s_barrier
	s_add_i32 s52, s79, s61
	v_lshl_add_u64 v[178:179], v[178:179], 0, s[18:19]
	s_mov_b32 m0, s52
	ds_read_b128 v[188:191], v186 offset:49152
	ds_read_b128 v[192:195], v186 offset:49168
	ds_read_b128 v[196:199], v186 offset:51200
	ds_read_b128 v[200:203], v186 offset:51216
	ds_read_b128 v[204:207], v186 offset:53248
	ds_read_b128 v[208:211], v186 offset:53264
	ds_read_b128 v[212:215], v186 offset:55296
	ds_read_b128 v[216:219], v186 offset:55312
	global_load_lds_dwordx4 v[178:179], off
	s_add_i32 m0, s52, 0x2000
	s_add_u32 s50, s50, 0x40080
	v_lshl_add_u64 v[178:179], v[180:181], 0, s[18:19]
	s_addc_u32 s51, s51, 0
	s_add_i32 s52, s80, s61
	global_load_lds_dwordx4 v[178:179], off
	v_lshl_add_u64 v[178:179], s[50:51], 0, v[164:165]
	s_mov_b32 m0, s52
	s_nop 0
	global_load_lds_dwordx4 v[178:179], off
	v_lshl_add_u64 v[178:179], s[50:51], 0, v[166:167]
	s_add_i32 m0, s52, 0x2000
	s_nop 0
	global_load_lds_dwordx4 v[178:179], off
	v_lshl_add_u64 v[178:179], v[182:183], 0, s[18:19]
	s_mov_b32 m0, s67
	s_nop 0
	global_load_lds_dwordx4 v[178:179], off
	v_lshl_add_u64 v[178:179], v[184:185], 0, s[18:19]
	s_mov_b32 m0, s68
	s_nop 0
	global_load_lds_dwordx4 v[178:179], off
	s_and_b64 vcc, exec, s[16:17]
	s_cbranch_vccz .Ldefer_g2_3
	s_waitcnt vmcnt(8)
.Ldefer_g2_3:
	s_waitcnt lgkmcnt(0)
	s_barrier
	s_setprio 1
	s_waitcnt lgkmcnt(0)
	v_mfma_scale_f32_16x16x128_f8f6f4 v[118:121], v[26:33], v[188:195], v[118:121], v187, v187 op_sel_hi:[0,0,0]
	v_mfma_scale_f32_16x16x128_f8f6f4 v[114:117], v[18:25], v[188:195], v[114:117], v187, v187 op_sel_hi:[0,0,0]
	v_mfma_scale_f32_16x16x128_f8f6f4 v[86:89], v[26:33], v[196:203], v[86:89], v187, v187 op_sel_hi:[0,0,0]
	v_mfma_scale_f32_16x16x128_f8f6f4 v[82:85], v[18:25], v[196:203], v[82:85], v187, v187 op_sel_hi:[0,0,0]
	v_mfma_scale_f32_16x16x128_f8f6f4 v[66:69], v[26:33], v[204:211], v[66:69], v187, v187 op_sel_hi:[0,0,0]
	v_mfma_scale_f32_16x16x128_f8f6f4 v[62:65], v[18:25], v[204:211], v[62:65], v187, v187 op_sel_hi:[0,0,0]
	v_mfma_scale_f32_16x16x128_f8f6f4 v[42:45], v[26:33], v[212:219], v[42:45], v187, v187 op_sel_hi:[0,0,0]
	v_mfma_scale_f32_16x16x128_f8f6f4 v[38:41], v[18:25], v[212:219], v[38:41], v187, v187 op_sel_hi:[0,0,0]
	s_setprio 0
	s_setprio 1
	v_mfma_scale_f32_16x16x128_f8f6f4 v[126:129], v[10:17], v[188:195], v[126:129], v187, v187 op_sel_hi:[0,0,0]
	v_mfma_scale_f32_16x16x128_f8f6f4 v[122:125], v[2:9], v[188:195], v[122:125], v187, v187 op_sel_hi:[0,0,0]
	v_mfma_scale_f32_16x16x128_f8f6f4 v[94:97], v[10:17], v[196:203], v[94:97], v187, v187 op_sel_hi:[0,0,0]
	v_mfma_scale_f32_16x16x128_f8f6f4 v[90:93], v[2:9], v[196:203], v[90:93], v187, v187 op_sel_hi:[0,0,0]
	v_mfma_scale_f32_16x16x128_f8f6f4 v[78:81], v[10:17], v[204:211], v[78:81], v187, v187 op_sel_hi:[0,0,0]
	v_mfma_scale_f32_16x16x128_f8f6f4 v[74:77], v[2:9], v[204:211], v[74:77], v187, v187 op_sel_hi:[0,0,0]
	v_mfma_scale_f32_16x16x128_f8f6f4 v[46:49], v[10:17], v[212:219], v[46:49], v187, v187 op_sel_hi:[0,0,0]
	v_mfma_scale_f32_16x16x128_f8f6f4 v[34:37], v[2:9], v[212:219], v[34:37], v187, v187 op_sel_hi:[0,0,0]
	s_setprio 0
	s_waitcnt vmcnt(8)
	s_barrier
	s_add_i32 s50, s35, 2
	s_add_u32 s48, s48, 0x100
	s_addc_u32 s49, s49, 0
	v_lshl_add_u64 v[176:177], v[176:177], 0, s[22:23]
	v_lshl_add_u64 v[174:175], v[174:175], 0, s[22:23]
	s_cmp_ge_i32 s35, s76
	s_mov_b32 s35, s50
	s_cbranch_scc0 .LBB0_1092
	s_nop 15
	s_nop 15
	s_and_b64 vcc, exec, s[20:21]
	s_cbranch_vccz .LBB0_1095
	s_barrier
